# attention steady loop: waves 4-7 run a body with the exp groups moved to the last eight PV MFMA gaps (complementary VALU/MFMA segments per SIMD)
# speedup vs baseline: 1.0081x; 1.0019x over previous
; #define WAIT_BAR(N) asm volatile("s_waitcnt vmcnt(" #N ") lgkmcnt(0)\n\ts_barrier":::"memory")
;   #define DMA_K(t,slot) glds16(ksrc+(long)(t)*KVBLK*DM,(unsigned)__builtin_amdgcn_readfirstlane(kdst+(slot)))
;   #define DMA_V(t,slot) do{ glds16(vsrc+(long)(t)*KVBLK*DM,(unsigned)__builtin_amdgcn_readfirstlane(vdst+2*(slot))); glds16(vsrc+64+(long)(t)*KVBLK*DM,(unsigned)__builtin_amdgcn_readfirstlane(vdst+2*(slot)+8192)); }while(0)
;   #define CMASK(P0,P1,t) do{int jb_=(t)-(NT-4); if(band&&jb_>=0)cmask(P0,P1,jb_,qrel,hi);}while(0)
;   #define START(P0,P1) do{ resc=false; \
;     { const float nm_=abase; \
;       _Pragma("unroll") for(int r=0;r<16;++r){ const float kc_=(float)((r&3)+8*(r>>2)); P0[r]=__builtin_fmaf(slope2,kc_,P0[r]+nm_); P1[r]=__builtin_fmaf(slope2,kc_+32.f,P1[r]+nm_); } } \
;     _Pragma("unroll") for(int r=0;r<16;++r)P0[r]=__builtin_amdgcn_exp2f(P0[r]); }while(0)
;   #define ROT() do{sl_prev=sl_cur;sl_cur=sl_next;sl_next=(sl_next==(NSLOT-1)*SLOTB)?0:sl_next+SLOTB;}while(0)
;   #define CMASK(P0,P1,t) do{}while(0)
;   #define CMASK(P0,P1,t) do{int jb_=(t)-(NT-4); if(band&&jb_>=0)cmask(P0,P1,jb_,qrel,hi);}while(0)
; template<int THRL> __device__ __forceinline__ void attn_unit(int hq,int hv,int qb,const bf16*Q,const bf16*__restrict__ K,const bf16*__restrict__ V,bf16*O,const float slope2,const int t0,const int ntiles,const bool band,float*Lout,const float bref,char*shm){
;     ...
;   const float dstep=64.f*slope2; const float abase=slope2*(float)(64*t0+4*hi-(q0+qrel))-bref;
;   float l_reg=0.f;f32x16 o[4];o[0]=f32x16{};o[1]=f32x16{};o[2]=f32x16{};o[3]=f32x16{};const f32x16 negm=f32x16{};
;     ...
;   bool resc=false;
;     ...
;   f32x16 pA0,pA1,pB0,pB1;
;   int sl_prev=0,sl_cur=0,sl_next=SLOTB;
;     ...
;   DMA_K(2,2*SLOTB);
;   WAIT_BAR(4);
;   qkt(pA0,pA1,Kbase,qr,negm,r32,hi);asm volatile("s_nop 15\n\ts_nop 7":"+v"(pA0),"+v"(pA1));CMASK(pA0,pA1,0);
;   START(pA0,pA1);
;   _Pragma("unroll") for(int r=0;r<16;++r)pA1[r]=__builtin_amdgcn_exp2f(pA1[r]);
;   WAIT_BAR(0);
;   DMA_K(3,0);DMA_V(1,SLOTB);
;   ROT();
;   kload8(kf,kp0+sl_cur);
;   WAIT_BAR(3);
;     ...
;   int t=1;
;     ...
;   for(;t+5<NT;t+=2){
.LBB0_284:
	v_lshlrev_b32_e32 v34, 1, v32
	v_and_b32_e32 v254, 32, v34
	v_lshrrev_b32_e32 v34, 2, v32
	v_and_or_b32 v34, v34, 3, v250
	v_lshlrev_b32_e32 v231, 6, v34
	v_lshl_or_b32 v34, s8, 6, v250
	v_add_u32_e32 v230, s4, v252
	v_sub_u32_e32 v34, v34, v230
	v_cvt_f32_i32_e32 v34, v34
	s_waitcnt vmcnt(0) lgkmcnt(0)
	s_barrier
	s_mov_b64 vcc, 0x60000
	s_cmp_lg_u32 0, -1
	v_fma_f32 v251, v245, v34, -s5
	v_add_f32_e32 v0, v251, v0
	v_add_f32_e32 v1, v251, v1
	v_fmac_f32_e32 v0, 0, v245
	v_add_f32_e32 v1, v245, v1
	v_exp_f32_e32 v96, v0
	v_exp_f32_e32 v97, v1
	v_lshl_add_u64 v[0:1], v[232:233], 0, vcc
	s_mov_b32 s39, m0
	s_mov_b32 m0, s16
	s_nop 0
	global_load_lds_dwordx4 v[0:1], off
	s_mov_b32 m0, s39
	s_cselect_b32 s39, 0, 0
	s_mov_b64 vcc, 0x20000
	s_add_i32 s10, s39, s10
	v_lshl_add_u64 v[0:1], v[234:235], 0, vcc
	s_add_i32 s39, s10, 0xa000
	s_mov_b32 s57, m0
	s_mov_b32 m0, s39
	s_nop 0
	global_load_lds_dwordx4 v[0:1], off
	s_mov_b32 m0, s57
	s_mov_b64 vcc, 0x20080
	v_lshl_add_u64 v[0:1], v[234:235], 0, vcc
	s_add_i32 s10, s10, 0xc000
	s_mov_b32 s39, m0
	s_mov_b32 m0, s10
	s_nop 0
	global_load_lds_dwordx4 v[0:1], off
	s_mov_b32 m0, s39
	ds_read_b128 v[204:207], v236 offset:8192
	ds_read_b128 v[196:199], v236 offset:8704
	ds_read_b128 v[200:203], v236 offset:10240
	ds_read_b128 v[188:191], v236 offset:10752
	ds_read_b128 v[192:195], v236 offset:12288
	ds_read_b128 v[180:183], v236 offset:12800
	ds_read_b128 v[184:187], v236 offset:14336
	ds_read_b128 v[176:179], v236 offset:14848
	v_add_f32_e32 v16, v251, v16
	v_add_f32_e32 v17, v251, v17
	v_add_f32_e32 v2, v251, v2
	v_add_f32_e32 v18, v251, v18
	v_add_f32_e32 v3, v251, v3
	v_add_f32_e32 v19, v251, v19
	v_add_f32_e32 v4, v251, v4
	v_add_f32_e32 v20, v251, v20
	v_add_f32_e32 v5, v251, v5
	v_add_f32_e32 v21, v251, v21
	v_add_f32_e32 v6, v251, v6
	v_add_f32_e32 v22, v251, v22
	v_add_f32_e32 v7, v251, v7
	v_add_f32_e32 v23, v251, v23
	v_add_f32_e32 v8, v251, v8
	v_add_f32_e32 v24, v251, v24
	v_add_f32_e32 v9, v251, v9
	v_add_f32_e32 v25, v251, v25
	v_add_f32_e32 v10, v251, v10
	v_add_f32_e32 v26, v251, v26
	v_add_f32_e32 v11, v251, v11
	v_add_f32_e32 v27, v251, v27
	v_add_f32_e32 v12, v251, v12
	v_add_f32_e32 v28, v251, v28
	v_add_f32_e32 v13, v251, v13
	v_add_f32_e32 v29, v251, v29
	v_add_f32_e32 v14, v251, v14
	v_add_f32_e32 v30, v251, v30
	v_add_f32_e32 v15, v251, v15
	v_add_f32_e32 v31, v251, v31
	v_fmac_f32_e32 v16, 0x42000000, v245
	v_fmac_f32_e32 v17, 0x42040000, v245
	v_fmac_f32_e32 v2, 2.0, v245
	v_fmac_f32_e32 v18, 0x42080000, v245
	v_fmac_f32_e32 v3, 0x40400000, v245
	v_fmac_f32_e32 v19, 0x420c0000, v245
	v_fmac_f32_e32 v4, 0x41000000, v245
	v_fmac_f32_e32 v20, 0x42200000, v245
	v_fmac_f32_e32 v5, 0x41100000, v245
	v_fmac_f32_e32 v21, 0x42240000, v245
	v_fmac_f32_e32 v6, 0x41200000, v245
	v_fmac_f32_e32 v22, 0x42280000, v245
	v_fmac_f32_e32 v7, 0x41300000, v245
	v_fmac_f32_e32 v23, 0x422c0000, v245
	v_fmac_f32_e32 v8, 0x41800000, v245
	v_fmac_f32_e32 v24, 0x42400000, v245
	v_fmac_f32_e32 v9, 0x41880000, v245
	v_fmac_f32_e32 v25, 0x42440000, v245
	v_fmac_f32_e32 v10, 0x41900000, v245
	v_fmac_f32_e32 v26, 0x42480000, v245
	v_fmac_f32_e32 v11, 0x41980000, v245
	v_fmac_f32_e32 v27, 0x424c0000, v245
	v_fmac_f32_e32 v12, 0x41c00000, v245
	v_fmac_f32_e32 v28, 0x42600000, v245
	v_fmac_f32_e32 v13, 0x41c80000, v245
	v_fmac_f32_e32 v29, 0x42640000, v245
	v_fmac_f32_e32 v14, 0x41d00000, v245
	v_fmac_f32_e32 v30, 0x42680000, v245
	v_fmac_f32_e32 v15, 0x41d80000, v245
	v_fmac_f32_e32 v31, 0x426c0000, v245
	v_exp_f32_e32 v98, v2
	v_exp_f32_e32 v99, v3
	v_exp_f32_e32 v100, v4
	v_exp_f32_e32 v101, v5
	v_exp_f32_e32 v102, v6
	v_exp_f32_e32 v103, v7
	v_exp_f32_e32 v104, v8
	v_exp_f32_e32 v105, v9
	v_exp_f32_e32 v106, v10
	v_exp_f32_e32 v107, v11
	v_exp_f32_e32 v108, v12
	v_exp_f32_e32 v109, v13
	v_exp_f32_e32 v110, v14
	v_exp_f32_e32 v111, v15
	v_exp_f32_e32 v80, v16
	v_exp_f32_e32 v81, v17
	v_exp_f32_e32 v82, v18
	v_exp_f32_e32 v83, v19
	v_exp_f32_e32 v84, v20
	v_exp_f32_e32 v85, v21
	v_exp_f32_e32 v86, v22
	v_exp_f32_e32 v87, v23
	v_exp_f32_e32 v88, v24
	v_exp_f32_e32 v89, v25
	v_exp_f32_e32 v90, v26
	v_exp_f32_e32 v91, v27
	v_exp_f32_e32 v92, v28
	v_exp_f32_e32 v93, v29
	v_exp_f32_e32 v94, v30
	v_exp_f32_e32 v95, v31
	s_waitcnt vmcnt(3) lgkmcnt(0)
	s_barrier
	v_add_u32_e32 v35, 0, v254
	v_writelane_b32 v255, s92, 24
	v_mov_b32_e32 v241, 0x260
	s_mov_b32 s38, 1
	v_add3_u32 v240, v35, v253, v231
	v_mul_f32_e32 v229, 0x42800000, v245
	s_mov_b32 s9, 0
	s_cmp_lt_i32 s87, 7
	s_cbranch_scc1 .LBB0_287
	s_lshl_b64 vcc, s[64:65], 8
	s_lshl_b64 s[76:77], s[76:77], 1
	s_add_u32 s76, s76, vcc_lo
	s_addc_u32 s77, s77, vcc_hi
	s_lshl_b32 s9, s88, 9
	s_and_b32 s9, s9, 0x18000
	s_lshl_b64 s[74:75], s[74:75], 1
	v_and_b32_e32 v0, 3, v32
	v_lshl_or_b32 v2, v33, 11, s9
	s_add_u32 s9, s12, s72
	v_lshlrev_b32_e32 v0, 4, v0
	v_mov_b32_e32 v1, v221
	s_addc_u32 s10, s13, s73
	v_lshl_add_u64 v[0:1], s[76:77], 0, v[0:1]
	v_mov_b32_e32 v3, v221
	s_add_u32 s72, s9, s74
	v_lshl_add_u64 v[0:1], v[0:1], 0, v[2:3]
	s_addc_u32 s73, s10, s75
	v_mov_b32_e32 v64, 0
	v_lshl_add_u64 v[208:209], s[12:13], 0, v[0:1]
	v_lshl_add_u64 v[210:211], s[72:73], 0, v[220:221]
	s_movk_i32 s57, 0x4000
	s_movk_i32 s92, 0x2000
	s_mov_b32 s39, 0
	v_mov_b32_e32 v32, 0
	v_mov_b32_e32 v33, v64
	v_mov_b32_e32 v34, v64
	v_mov_b32_e32 v35, v64
	v_mov_b32_e32 v36, v64
	v_mov_b32_e32 v37, v64
	v_mov_b32_e32 v38, v64
	v_mov_b32_e32 v39, v64
	v_mov_b32_e32 v40, v64
	v_mov_b32_e32 v41, v64
	v_mov_b32_e32 v42, v64
	v_mov_b32_e32 v43, v64
	v_mov_b32_e32 v44, v64
	v_mov_b32_e32 v45, v64
	v_mov_b32_e32 v46, v64
	v_mov_b32_e32 v47, v64
	v_mov_b32_e32 v48, 0
	v_mov_b32_e32 v49, v64
	v_mov_b32_e32 v50, v64
	v_mov_b32_e32 v51, v64
	v_mov_b32_e32 v52, v64
	v_mov_b32_e32 v53, v64
	v_mov_b32_e32 v54, v64
	v_mov_b32_e32 v55, v64
	v_mov_b32_e32 v56, v64
	v_mov_b32_e32 v57, v64
	v_mov_b32_e32 v58, v64
	v_mov_b32_e32 v59, v64
	v_mov_b32_e32 v60, v64
	v_mov_b32_e32 v61, v64
	v_mov_b32_e32 v62, v64
	v_mov_b32_e32 v63, v64
	v_mov_b32_e32 v0, 0
	v_mov_b32_e32 v1, v64
	v_mov_b32_e32 v2, v64
	v_mov_b32_e32 v3, v64
	v_mov_b32_e32 v4, v64
	v_mov_b32_e32 v5, v64
	v_mov_b32_e32 v6, v64
	v_mov_b32_e32 v7, v64
	v_mov_b32_e32 v8, v64
	v_mov_b32_e32 v9, v64
	v_mov_b32_e32 v10, v64
	v_mov_b32_e32 v11, v64
	v_mov_b32_e32 v12, v64
	v_mov_b32_e32 v13, v64
	v_mov_b32_e32 v14, v64
	v_mov_b32_e32 v15, v64
	v_mov_b32_e32 v16, 0
	v_mov_b32_e32 v17, v64
	v_mov_b32_e32 v18, v64
	v_mov_b32_e32 v19, v64
	v_mov_b32_e32 v20, v64
	v_mov_b32_e32 v21, v64
	v_mov_b32_e32 v22, v64
	v_mov_b32_e32 v23, v64
	v_mov_b32_e32 v24, v64
	v_mov_b32_e32 v25, v64
	v_mov_b32_e32 v26, v64
	v_mov_b32_e32 v27, v64
	v_mov_b32_e32 v28, v64
	v_mov_b32_e32 v29, v64
	v_mov_b32_e32 v30, v64
	v_mov_b32_e32 v31, v64
	v_readfirstlane_b32 s32, v227
	s_nop 3
	s_cmpk_ge_u32 s32, 0x100
	s_cbranch_scc1 .Lattn_t286

.Lattn_t286:
	s_mov_b32 s10, s38
	s_mov_b32 s9, s57
	s_mov_b32 s38, s92
	v_lshl_add_u32 v212, s39, 1, v240
	ds_read_b64_tr_b16 v[214:215], v212 offset:24576
	ds_read_b64_tr_b16 v[216:217], v212 offset:25088
	v_add_f32_e32 v65, v96, v97
	v_add_f32_e32 v65, v98, v65
	v_add_f32_e32 v65, v99, v65
	v_add_f32_e32 v65, v100, v65
	v_add_f32_e32 v65, v101, v65
	v_cvt_pk_bf16_f32 v156, v96, v97
	v_cvt_pk_bf16_f32 v157, v98, v99
	s_waitcnt lgkmcnt(9)
	v_mfma_f32_32x32x16_bf16 v[128:143], v[204:207], v[172:175], 0
	ds_read_b64_tr_b16 v[204:205], v212 offset:28672
	ds_read_b64_tr_b16 v[206:207], v212 offset:29184
	v_add_f32_e32 v65, v102, v65
	v_add_f32_e32 v65, v103, v65
	v_add_f32_e32 v65, v104, v65
	v_add_f32_e32 v65, v105, v65
	v_cvt_pk_bf16_f32 v158, v100, v101
	v_cvt_pk_bf16_f32 v159, v102, v103
	s_waitcnt lgkmcnt(10)
	v_mfma_f32_32x32x16_bf16 v[112:127], v[196:199], v[172:175], 0
	ds_read_b64_tr_b16 v[196:197], v212 offset:25600
	ds_read_b64_tr_b16 v[198:199], v212 offset:26112
	v_add_f32_e32 v65, v106, v65
	v_add_f32_e32 v65, v107, v65
	v_add_f32_e32 v65, v108, v65
	v_add_f32_e32 v65, v109, v65
	v_cvt_pk_bf16_f32 v152, v104, v105
	v_cvt_pk_bf16_f32 v153, v106, v107
	s_waitcnt lgkmcnt(11)
	v_mfma_f32_32x32x16_bf16 v[128:143], v[200:203], v[168:171], v[128:143]
	ds_read_b64_tr_b16 v[74:75], v212 offset:29696
	ds_read_b64_tr_b16 v[76:77], v212 offset:30208
	v_add_f32_e32 v65, v110, v65
	v_add_f32_e32 v65, v111, v65
	v_add_f32_e32 v65, v80, v65
	v_add_f32_e32 v65, v81, v65
	v_cvt_pk_bf16_f32 v154, v108, v109
	v_cvt_pk_bf16_f32 v155, v110, v111
	s_waitcnt lgkmcnt(12)
	v_mfma_f32_32x32x16_bf16 v[112:127], v[188:191], v[168:171], v[112:127]
	ds_read_b64_tr_b16 v[66:67], v212 offset:26624
	ds_read_b64_tr_b16 v[68:69], v212 offset:27136
	v_add_f32_e32 v65, v82, v65
	v_add_f32_e32 v65, v83, v65
	v_add_f32_e32 v65, v84, v65
	v_add_f32_e32 v65, v85, v65
	v_cvt_pk_bf16_f32 v148, v80, v81
	v_cvt_pk_bf16_f32 v149, v82, v83
	s_waitcnt lgkmcnt(13)
	v_mfma_f32_32x32x16_bf16 v[128:143], v[192:195], v[164:167], v[128:143]
	ds_read_b64_tr_b16 v[96:97], v212 offset:30720
	ds_read_b64_tr_b16 v[98:99], v212 offset:31232
	v_add_f32_e32 v65, v86, v65
	v_add_f32_e32 v65, v87, v65
	v_add_f32_e32 v65, v88, v65
	v_add_f32_e32 v65, v89, v65
	v_cvt_pk_bf16_f32 v150, v84, v85
	v_cvt_pk_bf16_f32 v151, v86, v87
	s_waitcnt lgkmcnt(14)
	v_mfma_f32_32x32x16_bf16 v[112:127], v[180:183], v[164:167], v[112:127]
	ds_read_b64_tr_b16 v[82:83], v212 offset:27648
	ds_read_b64_tr_b16 v[84:85], v212 offset:28160
	v_add_f32_e32 v65, v90, v65
	v_add_f32_e32 v65, v91, v65
	v_add_f32_e32 v65, v92, v65
	v_add_f32_e32 v65, v93, v65
	v_cvt_pk_bf16_f32 v144, v88, v89
	v_cvt_pk_bf16_f32 v145, v90, v91
	s_waitcnt lgkmcnt(14)
	v_mfma_f32_32x32x16_bf16 v[128:143], v[184:187], v[160:163], v[128:143]
	ds_read_b64_tr_b16 v[70:71], v212 offset:31744
	ds_read_b64_tr_b16 v[72:73], v212 offset:32256
	v_add_f32_e32 v65, v94, v65
	v_add_f32_e32 v65, v95, v65
	v_add_f32_e32 v65, 0, v65
	v_cvt_pk_bf16_f32 v146, v92, v93
	v_cvt_pk_bf16_f32 v147, v94, v95
	v_mfma_f32_32x32x16_bf16 v[112:127], v[176:179], v[160:163], v[112:127]
	v_lshl_add_u64 v[202:203], v[210:211], 0, s[70:71]
	v_lshl_add_u64 v[78:79], v[202:203], 0, s[48:49]
	s_add_i32 s39, s92, s16
	v_lshl_add_u64 v[200:201], v[208:209], 0, s[70:71]
	s_mov_b32 s57, m0
	s_mov_b32 m0, s39
	s_nop 0
	global_load_lds_dwordx4 v[78:79], off
	s_mov_b32 m0, s57
	v_lshl_add_u64 v[78:79], v[200:201], 0, s[50:51]
	s_lshl_b32 s39, s9, 1
	s_add_i32 s39, s39, s17
	s_mov_b32 s57, m0
	s_mov_b32 m0, s39
	s_nop 0
	global_load_lds_dwordx4 v[78:79], off
	s_mov_b32 m0, s57
	v_lshl_add_u64 v[78:79], v[200:201], 0, s[52:53]
	s_addk_i32 s39, 0x2000
	s_mov_b32 s57, m0
	s_mov_b32 m0, s39
	s_nop 0
	global_load_lds_dwordx4 v[78:79], off
	s_mov_b32 m0, s57
	v_cvt_f32_u32_e32 v78, s10
	v_fma_f32 v213, v229, v78, v251
	s_waitcnt lgkmcnt(14)
	v_mfma_f32_32x32x16_bf16 v[32:47], v[156:159], v[214:217], v[32:47]
	ds_read_b64_tr_b16 v[90:91], v212 offset:32768
	ds_read_b64_tr_b16 v[92:93], v212 offset:33280
	s_waitcnt lgkmcnt(14)
	v_mfma_f32_32x32x16_bf16 v[48:63], v[156:159], v[204:207], v[48:63]
	ds_read_b64_tr_b16 v[100:101], v212 offset:36864
	ds_read_b64_tr_b16 v[102:103], v212 offset:37376
	v_add_u32_e32 v94, s9, v236
	ds_read_b128 v[86:89], v94
	ds_read_b128 v[78:81], v94 offset:512
	s_waitcnt lgkmcnt(14)
	v_mfma_f32_32x32x16_bf16 v[32:47], v[152:155], v[196:199], v[32:47]
	ds_read_b64_tr_b16 v[104:105], v212 offset:33792
	ds_read_b64_tr_b16 v[106:107], v212 offset:34304
	ds_read_b128 v[188:191], v94 offset:2048
	ds_read_b128 v[176:179], v94 offset:2560
	v_mfma_f32_32x32x16_bf16 v[48:63], v[152:155], v[74:77], v[48:63]
	ds_read_b64_tr_b16 v[108:109], v212 offset:37888
	ds_read_b64_tr_b16 v[110:111], v212 offset:38400
	ds_read_b128 v[184:187], v94 offset:4096
	ds_read_b128 v[74:77], v94 offset:4608
	s_waitcnt lgkmcnt(14)
	v_mfma_f32_32x32x16_bf16 v[32:47], v[148:151], v[66:69], v[32:47]
	ds_read_b64_tr_b16 v[192:193], v212 offset:34816
	ds_read_b64_tr_b16 v[194:195], v212 offset:35328
	ds_read_b128 v[180:183], v94 offset:6144
	ds_read_b128 v[66:69], v94 offset:6656
	v_mfma_f32_32x32x16_bf16 v[48:63], v[148:151], v[96:99], v[48:63]
	ds_read_b64_tr_b16 v[94:95], v212 offset:38912
	ds_read_b64_tr_b16 v[96:97], v212 offset:39424
	v_mfma_f32_32x32x16_bf16 v[32:47], v[144:147], v[82:85], v[32:47]
	ds_read_b64_tr_b16 v[82:83], v212 offset:35840
	ds_read_b64_tr_b16 v[84:85], v212 offset:36352
	v_mfma_f32_32x32x16_bf16 v[48:63], v[144:147], v[70:73], v[48:63]
	ds_read_b64_tr_b16 v[70:71], v212 offset:39936
	ds_read_b64_tr_b16 v[72:73], v212 offset:40448
	s_waitcnt lgkmcnt(14)
	v_mfma_f32_32x32x16_bf16 v[0:15], v[156:159], v[90:93], v[0:15]
	v_add_f32_e32 v212, v213, v128
	v_fmac_f32_e32 v212, 0, v245
	v_exp_f32_e32 v128, v212
	v_add_f32_e32 v212, v213, v129
	v_add_f32_e32 v212, v245, v212
	v_exp_f32_e32 v129, v212
	v_add_f32_e32 v212, v213, v130
	v_fmac_f32_e32 v212, 2.0, v245
	v_exp_f32_e32 v130, v212
	v_add_f32_e32 v212, v213, v131
	v_fmac_f32_e32 v212, 0x40400000, v245
	v_exp_f32_e32 v131, v212
	v_mfma_f32_32x32x16_bf16 v[16:31], v[156:159], v[100:103], v[16:31]
	v_add_f32_e32 v212, v213, v132
	v_fmac_f32_e32 v212, 0x41000000, v245
	v_exp_f32_e32 v132, v212
	v_add_f32_e32 v212, v213, v133
	v_fmac_f32_e32 v212, 0x41100000, v245
	v_exp_f32_e32 v133, v212
	v_add_f32_e32 v212, v213, v134
	v_fmac_f32_e32 v212, 0x41200000, v245
	v_exp_f32_e32 v134, v212
	v_add_f32_e32 v212, v213, v135
	v_fmac_f32_e32 v212, 0x41300000, v245
	v_exp_f32_e32 v135, v212
	v_mfma_f32_32x32x16_bf16 v[0:15], v[152:155], v[104:107], v[0:15]
	v_add_f32_e32 v212, v213, v136
	v_fmac_f32_e32 v212, 0x41800000, v245
	v_exp_f32_e32 v136, v212
	v_add_f32_e32 v212, v213, v137
	v_fmac_f32_e32 v212, 0x41880000, v245
	v_exp_f32_e32 v137, v212
	v_add_f32_e32 v212, v213, v138
	v_fmac_f32_e32 v212, 0x41900000, v245
	v_exp_f32_e32 v138, v212
	v_add_f32_e32 v212, v213, v139
	v_fmac_f32_e32 v212, 0x41980000, v245
	v_exp_f32_e32 v139, v212
	s_waitcnt lgkmcnt(12)
	v_mfma_f32_32x32x16_bf16 v[16:31], v[152:155], v[108:111], v[16:31]
	v_add_f32_e32 v212, v213, v140
	v_fmac_f32_e32 v212, 0x41c00000, v245
	v_exp_f32_e32 v140, v212
	v_add_f32_e32 v212, v213, v141
	v_fmac_f32_e32 v212, 0x41c80000, v245
	v_exp_f32_e32 v141, v212
	v_add_f32_e32 v212, v213, v142
	v_fmac_f32_e32 v212, 0x41d00000, v245
	v_exp_f32_e32 v142, v212
	v_add_f32_e32 v212, v213, v143
	v_fmac_f32_e32 v212, 0x41d80000, v245
	v_exp_f32_e32 v143, v212
	s_waitcnt lgkmcnt(8)
	v_mfma_f32_32x32x16_bf16 v[0:15], v[148:151], v[192:195], v[0:15]
	v_add_f32_e32 v212, v213, v112
	v_fmac_f32_e32 v212, 0x42000000, v245
	v_exp_f32_e32 v112, v212
	v_add_f32_e32 v212, v213, v113
	v_fmac_f32_e32 v212, 0x42040000, v245
	v_exp_f32_e32 v113, v212
	v_add_f32_e32 v212, v213, v114
	v_fmac_f32_e32 v212, 0x42080000, v245
	v_exp_f32_e32 v114, v212
	v_add_f32_e32 v212, v213, v115
	v_fmac_f32_e32 v212, 0x420c0000, v245
	v_exp_f32_e32 v115, v212
	s_waitcnt lgkmcnt(4)
	v_mfma_f32_32x32x16_bf16 v[16:31], v[148:151], v[94:97], v[16:31]
	v_add_f32_e32 v212, v213, v116
	v_fmac_f32_e32 v212, 0x42200000, v245
	v_exp_f32_e32 v116, v212
	v_add_f32_e32 v212, v213, v117
	v_fmac_f32_e32 v212, 0x42240000, v245
	v_exp_f32_e32 v117, v212
	v_add_f32_e32 v212, v213, v118
	v_fmac_f32_e32 v212, 0x42280000, v245
	v_exp_f32_e32 v118, v212
	v_add_f32_e32 v212, v213, v119
	v_fmac_f32_e32 v212, 0x422c0000, v245
	v_exp_f32_e32 v119, v212
	s_waitcnt lgkmcnt(2)
	v_mfma_f32_32x32x16_bf16 v[0:15], v[144:147], v[82:85], v[0:15]
	v_add_f32_e32 v212, v213, v120
	v_fmac_f32_e32 v212, 0x42400000, v245
	v_exp_f32_e32 v120, v212
	v_add_f32_e32 v212, v213, v121
	v_fmac_f32_e32 v212, 0x42440000, v245
	v_exp_f32_e32 v121, v212
	v_add_f32_e32 v212, v213, v122
	v_fmac_f32_e32 v212, 0x42480000, v245
	v_exp_f32_e32 v122, v212
	v_add_f32_e32 v212, v213, v123
	v_fmac_f32_e32 v212, 0x424c0000, v245
	v_exp_f32_e32 v123, v212
	s_waitcnt lgkmcnt(0)
	v_mfma_f32_32x32x16_bf16 v[16:31], v[144:147], v[70:73], v[16:31]
	v_add_f32_e32 v212, v213, v124
	v_fmac_f32_e32 v212, 0x42600000, v245
	v_exp_f32_e32 v124, v212
	v_add_f32_e32 v212, v213, v125
	v_fmac_f32_e32 v212, 0x42640000, v245
	v_exp_f32_e32 v125, v212
	v_add_f32_e32 v212, v213, v126
	v_fmac_f32_e32 v212, 0x42680000, v245
	v_exp_f32_e32 v126, v212
	v_add_f32_e32 v212, v213, v127
	v_fmac_f32_e32 v212, 0x426c0000, v245
	v_exp_f32_e32 v127, v212
	s_waitcnt vmcnt(3) lgkmcnt(0)
	s_barrier
	s_add_i32 s39, s9, 0x2000
	s_cmpk_lg_i32 s9, 0x4000
	s_cselect_b32 s92, s39, 0
	v_lshl_add_u32 v212, s38, 1, v240
	ds_read_b64_tr_b16 v[196:197], v212 offset:24576
	ds_read_b64_tr_b16 v[198:199], v212 offset:25088
	v_mfma_f32_32x32x16_bf16 v[96:111], v[86:89], v[172:175], 0
	v_add_f32_e32 v70, v128, v129
	v_add_f32_e32 v70, v130, v70
	v_add_f32_e32 v70, v131, v70
	v_add_f32_e32 v70, v132, v70
	v_add_f32_e32 v70, v133, v70
	v_cvt_pk_bf16_f32 v156, v128, v129
	v_cvt_pk_bf16_f32 v157, v130, v131
	ds_read_b64_tr_b16 v[204:205], v212 offset:28672
	ds_read_b64_tr_b16 v[206:207], v212 offset:29184
	v_mfma_f32_32x32x16_bf16 v[80:95], v[78:81], v[172:175], 0
	v_add_f32_e32 v70, v134, v70
	v_add_f32_e32 v70, v135, v70
	v_add_f32_e32 v70, v136, v70
	v_add_f32_e32 v70, v137, v70
	v_cvt_pk_bf16_f32 v158, v132, v133
	v_cvt_pk_bf16_f32 v159, v134, v135
	ds_read_b64_tr_b16 v[192:193], v212 offset:25600
	ds_read_b64_tr_b16 v[194:195], v212 offset:26112
	v_mfma_f32_32x32x16_bf16 v[96:111], v[188:191], v[168:171], v[96:111]
	v_add_f32_e32 v70, v138, v70
	v_add_f32_e32 v70, v139, v70
	v_add_f32_e32 v70, v140, v70
	v_add_f32_e32 v70, v141, v70
	v_cvt_pk_bf16_f32 v152, v136, v137
	v_cvt_pk_bf16_f32 v153, v138, v139
	ds_read_b64_tr_b16 v[132:133], v212 offset:29696
	ds_read_b64_tr_b16 v[134:135], v212 offset:30208
	v_mfma_f32_32x32x16_bf16 v[80:95], v[176:179], v[168:171], v[80:95]
	v_add_f32_e32 v70, v142, v70
	v_add_f32_e32 v70, v143, v70
	v_add_f32_e32 v70, v112, v70
	v_add_f32_e32 v70, v113, v70
	v_cvt_pk_bf16_f32 v154, v140, v141
	v_cvt_pk_bf16_f32 v155, v142, v143
	ds_read_b64_tr_b16 v[128:129], v212 offset:26624
	ds_read_b64_tr_b16 v[130:131], v212 offset:27136
	v_mfma_f32_32x32x16_bf16 v[96:111], v[184:187], v[164:167], v[96:111]
	v_add_f32_e32 v70, v114, v70
	v_add_f32_e32 v70, v115, v70
	v_add_f32_e32 v70, v116, v70
	v_add_f32_e32 v70, v117, v70
	v_cvt_pk_bf16_f32 v148, v112, v113
	v_cvt_pk_bf16_f32 v149, v114, v115
	ds_read_b64_tr_b16 v[112:113], v212 offset:30720
	ds_read_b64_tr_b16 v[114:115], v212 offset:31232
	v_mfma_f32_32x32x16_bf16 v[80:95], v[74:77], v[164:167], v[80:95]
	v_add_f32_e32 v70, v118, v70
	v_add_f32_e32 v70, v119, v70
	v_add_f32_e32 v70, v120, v70
	v_add_f32_e32 v70, v121, v70
	v_cvt_pk_bf16_f32 v150, v116, v117
	v_cvt_pk_bf16_f32 v151, v118, v119
	ds_read_b64_tr_b16 v[74:75], v212 offset:27648
	ds_read_b64_tr_b16 v[76:77], v212 offset:28160
	v_mfma_f32_32x32x16_bf16 v[96:111], v[180:183], v[160:163], v[96:111]
	v_add_f32_e32 v70, v122, v70
	v_add_f32_e32 v70, v123, v70
	v_add_f32_e32 v70, v124, v70
	v_add_f32_e32 v78, v125, v70
	v_cvt_pk_bf16_f32 v144, v120, v121
	v_cvt_pk_bf16_f32 v145, v122, v123
	ds_read_b64_tr_b16 v[70:71], v212 offset:31744
	ds_read_b64_tr_b16 v[72:73], v212 offset:32256
	v_mfma_f32_32x32x16_bf16 v[80:95], v[66:69], v[160:163], v[80:95]
	v_add_f32_e32 v66, v126, v78
	v_add_f32_e32 v66, v127, v66
	v_add_f32_e32 v78, 0, v66
	v_cvt_pk_bf16_f32 v146, v124, v125
	v_cvt_pk_bf16_f32 v147, v126, v127
	v_lshl_add_u64 v[66:67], v[202:203], 0, s[54:55]
	s_add_i32 s38, s9, s16
	s_mov_b32 s39, m0
	s_mov_b32 m0, s38
	s_nop 0
	global_load_lds_dwordx4 v[66:67], off
	s_mov_b32 m0, s39
	s_lshl_b32 s39, s92, 1
	v_lshl_add_u64 v[66:67], v[200:201], 0, s[58:59]
	s_add_i32 s39, s39, s17
	s_mov_b32 s57, m0
	s_mov_b32 m0, s39
	s_nop 0
	global_load_lds_dwordx4 v[66:67], off
	s_mov_b32 m0, s57
	s_add_i32 s57, s10, 1
	v_cvt_f32_u32_e32 v68, s57
	v_lshl_add_u64 v[66:67], v[200:201], 0, s[60:61]
	s_addk_i32 s39, 0x2000
	s_mov_b32 s57, m0
	s_mov_b32 m0, s39
	s_nop 0
	global_load_lds_dwordx4 v[66:67], off
	s_mov_b32 m0, s57
	s_add_i32 s38, s10, 2
	v_fma_f32 v79, v229, v68, v251
	s_waitcnt lgkmcnt(14)
	v_mfma_f32_32x32x16_bf16 v[32:47], v[156:159], v[196:199], v[32:47]
	ds_read_b64_tr_b16 v[66:67], v212 offset:32768
	ds_read_b64_tr_b16 v[68:69], v212 offset:33280
	s_waitcnt lgkmcnt(14)
	v_mfma_f32_32x32x16_bf16 v[48:63], v[156:159], v[204:207], v[48:63]
	ds_read_b64_tr_b16 v[116:117], v212 offset:36864
	ds_read_b64_tr_b16 v[118:119], v212 offset:37376
	v_add_u32_e32 v136, s92, v236
	ds_read_b128 v[204:207], v136
	ds_read_b128 v[196:199], v136 offset:512
	s_waitcnt lgkmcnt(14)
	v_mfma_f32_32x32x16_bf16 v[32:47], v[152:155], v[192:195], v[32:47]
	ds_read_b64_tr_b16 v[120:121], v212 offset:33792
	ds_read_b64_tr_b16 v[122:123], v212 offset:34304
	ds_read_b128 v[200:203], v136 offset:2048
	ds_read_b128 v[188:191], v136 offset:2560
	v_mfma_f32_32x32x16_bf16 v[48:63], v[152:155], v[132:135], v[48:63]
	ds_read_b64_tr_b16 v[124:125], v212 offset:37888
	ds_read_b64_tr_b16 v[126:127], v212 offset:38400
	ds_read_b128 v[192:195], v136 offset:4096
	ds_read_b128 v[180:183], v136 offset:4608
	s_waitcnt lgkmcnt(14)
	v_mfma_f32_32x32x16_bf16 v[32:47], v[148:151], v[128:131], v[32:47]
	ds_read_b64_tr_b16 v[128:129], v212 offset:34816
	ds_read_b64_tr_b16 v[130:131], v212 offset:35328
	ds_read_b128 v[184:187], v136 offset:6144
	ds_read_b128 v[176:179], v136 offset:6656
	v_mfma_f32_32x32x16_bf16 v[48:63], v[148:151], v[112:115], v[48:63]
	ds_read_b64_tr_b16 v[112:113], v212 offset:38912
	ds_read_b64_tr_b16 v[114:115], v212 offset:39424
	v_mfma_f32_32x32x16_bf16 v[32:47], v[144:147], v[74:77], v[32:47]
	ds_read_b64_tr_b16 v[74:75], v212 offset:35840
	ds_read_b64_tr_b16 v[76:77], v212 offset:36352
	v_mfma_f32_32x32x16_bf16 v[48:63], v[144:147], v[70:73], v[48:63]
	ds_read_b64_tr_b16 v[70:71], v212 offset:39936
	ds_read_b64_tr_b16 v[72:73], v212 offset:40448
	s_waitcnt lgkmcnt(14)
; #define WAIT_BAR(N) asm volatile("s_waitcnt vmcnt(" #N ") lgkmcnt(0)\n\ts_barrier":::"memory")
;   #define RESC() do{ if(resc){ asm volatile("s_waitcnt lgkmcnt(0)":::"memory"); \
;       _Pragma("unroll") for(int d_=0;d_<2;++d_) _Pragma("unroll") for(int r=0;r<16;++r)o[d_][r]*=wsf[crow(r,hi)]; } }while(0)
;   #define ROT() do{sl_prev=sl_cur;sl_cur=sl_next;sl_next=(sl_next==(NSLOT-1)*SLOTB)?0:sl_next+SLOTB;}while(0)
; template<int THRL> __device__ __forceinline__ void attn_unit(int hq,int hv,int qb,const bf16*Q,const bf16*__restrict__ K,const bf16*__restrict__ V,bf16*O,const float slope2,const int t0,const int ntiles,const bool band,float*Lout,const float bref,char*shm){
;     ...
;   int t=1;
;     ...
;   for(;t+5<NT;t+=2){
;     STEP(pB0,pB1,pA0,pA1,t,true,true,true);     WAIT_BAR(3); RESC(); ROT();
;     STEP(pA0,pA1,pB0,pB1,t+1,true,true,true);   WAIT_BAR(3); RESC(); ROT();
;   }
	v_mfma_f32_32x32x16_bf16 v[0:15], v[156:159], v[66:69], v[0:15]
	v_add_f32_e32 v212, v79, v96
	v_fmac_f32_e32 v212, 0, v245
	v_exp_f32_e32 v96, v212
	v_add_f32_e32 v212, v79, v97
	v_add_f32_e32 v212, v245, v212
	v_exp_f32_e32 v97, v212
	v_add_f32_e32 v212, v79, v98
	v_fmac_f32_e32 v212, 2.0, v245
	v_exp_f32_e32 v98, v212
	v_add_f32_e32 v212, v79, v99
	v_fmac_f32_e32 v212, 0x40400000, v245
	v_exp_f32_e32 v99, v212
	v_mfma_f32_32x32x16_bf16 v[16:31], v[156:159], v[116:119], v[16:31]
	v_add_f32_e32 v100, v79, v100
	v_fmac_f32_e32 v100, 0x41000000, v245
	v_exp_f32_e32 v100, v100
	v_add_f32_e32 v101, v79, v101
	v_fmac_f32_e32 v101, 0x41100000, v245
	v_exp_f32_e32 v101, v101
	v_add_f32_e32 v102, v79, v102
	v_fmac_f32_e32 v102, 0x41200000, v245
	v_exp_f32_e32 v102, v102
	v_add_f32_e32 v103, v79, v103
	v_fmac_f32_e32 v103, 0x41300000, v245
	v_exp_f32_e32 v103, v103
	v_mfma_f32_32x32x16_bf16 v[0:15], v[152:155], v[120:123], v[0:15]
	v_add_f32_e32 v104, v79, v104
	v_fmac_f32_e32 v104, 0x41800000, v245
	v_exp_f32_e32 v104, v104
	v_add_f32_e32 v105, v79, v105
	v_fmac_f32_e32 v105, 0x41880000, v245
	v_exp_f32_e32 v105, v105
	v_add_f32_e32 v106, v79, v106
	v_fmac_f32_e32 v106, 0x41900000, v245
	v_exp_f32_e32 v106, v106
	v_add_f32_e32 v107, v79, v107
	v_fmac_f32_e32 v107, 0x41980000, v245
	v_exp_f32_e32 v107, v107
	s_waitcnt lgkmcnt(12)
	v_mfma_f32_32x32x16_bf16 v[16:31], v[152:155], v[124:127], v[16:31]
	v_add_f32_e32 v108, v79, v108
	v_fmac_f32_e32 v108, 0x41c00000, v245
	v_exp_f32_e32 v108, v108
	v_add_f32_e32 v109, v79, v109
	v_fmac_f32_e32 v109, 0x41c80000, v245
	v_exp_f32_e32 v109, v109
	v_add_f32_e32 v110, v79, v110
	v_fmac_f32_e32 v110, 0x41d00000, v245
	v_exp_f32_e32 v110, v110
	v_add_f32_e32 v111, v79, v111
	v_fmac_f32_e32 v111, 0x41d80000, v245
	v_exp_f32_e32 v111, v111
	s_waitcnt lgkmcnt(8)
	v_mfma_f32_32x32x16_bf16 v[0:15], v[148:151], v[128:131], v[0:15]
	v_add_f32_e32 v80, v79, v80
	v_fmac_f32_e32 v80, 0x42000000, v245
	v_exp_f32_e32 v80, v80
	v_add_f32_e32 v81, v79, v81
	v_fmac_f32_e32 v81, 0x42040000, v245
	v_exp_f32_e32 v81, v81
	v_add_f32_e32 v82, v79, v82
	v_fmac_f32_e32 v82, 0x42080000, v245
	v_exp_f32_e32 v82, v82
	v_add_f32_e32 v83, v79, v83
	v_fmac_f32_e32 v83, 0x420c0000, v245
	v_exp_f32_e32 v83, v83
	s_waitcnt lgkmcnt(4)
	v_mfma_f32_32x32x16_bf16 v[16:31], v[148:151], v[112:115], v[16:31]
	v_add_f32_e32 v84, v79, v84
	v_fmac_f32_e32 v84, 0x42200000, v245
	v_exp_f32_e32 v84, v84
	v_add_f32_e32 v85, v79, v85
	v_fmac_f32_e32 v85, 0x42240000, v245
	v_exp_f32_e32 v85, v85
	v_add_f32_e32 v86, v79, v86
	v_fmac_f32_e32 v86, 0x42280000, v245
	v_exp_f32_e32 v86, v86
	v_add_f32_e32 v87, v79, v87
	v_fmac_f32_e32 v87, 0x422c0000, v245
	v_exp_f32_e32 v87, v87
	s_waitcnt lgkmcnt(2)
	v_mfma_f32_32x32x16_bf16 v[0:15], v[144:147], v[74:77], v[0:15]
	v_add_f32_e32 v212, v79, v88
	v_fmac_f32_e32 v212, 0x42400000, v245
	v_exp_f32_e32 v88, v212
	v_add_f32_e32 v212, v79, v89
	v_fmac_f32_e32 v212, 0x42440000, v245
	v_exp_f32_e32 v89, v212
	v_add_f32_e32 v212, v79, v90
	v_fmac_f32_e32 v212, 0x42480000, v245
	v_exp_f32_e32 v90, v212
	v_add_f32_e32 v212, v79, v91
	v_fmac_f32_e32 v212, 0x424c0000, v245
	v_exp_f32_e32 v91, v212
	s_waitcnt lgkmcnt(0)
	v_mfma_f32_32x32x16_bf16 v[16:31], v[144:147], v[70:73], v[16:31]
	v_add_f32_e32 v212, v79, v92
	v_fmac_f32_e32 v212, 0x42600000, v245
	v_exp_f32_e32 v92, v212
	v_add_f32_e32 v212, v79, v93
	v_fmac_f32_e32 v212, 0x42640000, v245
	v_exp_f32_e32 v93, v212
	v_add_f32_e32 v212, v79, v94
	v_fmac_f32_e32 v212, 0x42680000, v245
	v_exp_f32_e32 v94, v212
	v_add_f32_e32 v212, v79, v95
	v_fmac_f32_e32 v212, 0x426c0000, v245
	v_exp_f32_e32 v95, v212
	s_add_i32 s39, s92, 0x2000
	s_waitcnt vmcnt(3) lgkmcnt(0)
	s_barrier
	s_cmpk_lg_i32 s92, 0x4000
	v_add_f32_e32 v64, v64, v65
	s_cselect_b32 s57, s39, 0
	s_add_i32 s10, s10, 7
	v_add_f32_e32 v64, v64, v78
	v_lshl_add_u64 v[208:209], v[208:209], 0, s[42:43]
	v_lshl_add_u64 v[210:211], v[210:211], 0, s[42:43]
	s_cmp_ge_i32 s10, s87
	s_mov_b32 s39, s9
	s_cbranch_scc0 .Lattn_t286
	s_branch .LBB0_288

; #define WAIT_BAR(N) asm volatile("s_waitcnt vmcnt(" #N ") lgkmcnt(0)\n\ts_barrier":::"memory")
;   #define DMA_K(t,slot) glds16(ksrc+(long)(t)*KVBLK*DM,(unsigned)__builtin_amdgcn_readfirstlane(kdst+(slot)))
;   #define DMA_V(t,slot) do{ glds16(vsrc+(long)(t)*KVBLK*DM,(unsigned)__builtin_amdgcn_readfirstlane(vdst+2*(slot))); glds16(vsrc+64+(long)(t)*KVBLK*DM,(unsigned)__builtin_amdgcn_readfirstlane(vdst+2*(slot)+8192)); }while(0)
;   #define CMASK(P0,P1,t) do{int jb_=(t)-(NT-4); if(band&&jb_>=0)cmask(P0,P1,jb_,qrel,hi);}while(0)
;   #define START(P0,P1) do{ resc=false; \
;     { const float nm_=abase; \
;       _Pragma("unroll") for(int r=0;r<16;++r){ const float kc_=(float)((r&3)+8*(r>>2)); P0[r]=__builtin_fmaf(slope2,kc_,P0[r]+nm_); P1[r]=__builtin_fmaf(slope2,kc_+32.f,P1[r]+nm_); } } \
;     _Pragma("unroll") for(int r=0;r<16;++r)P0[r]=__builtin_amdgcn_exp2f(P0[r]); }while(0)
;   #define ROT() do{sl_prev=sl_cur;sl_cur=sl_next;sl_next=(sl_next==(NSLOT-1)*SLOTB)?0:sl_next+SLOTB;}while(0)
;   #define CMASK(P0,P1,t) do{}while(0)
;   #define CMASK(P0,P1,t) do{int jb_=(t)-(NT-4); if(band&&jb_>=0)cmask(P0,P1,jb_,qrel,hi);}while(0)
; template<int THRL> __device__ __forceinline__ void attn_unit(int hq,int hv,int qb,const bf16*Q,const bf16*__restrict__ K,const bf16*__restrict__ V,bf16*O,const float slope2,const int t0,const int ntiles,const bool band,float*Lout,const float bref,char*shm){
;     ...
;   const float dstep=64.f*slope2; const float abase=slope2*(float)(64*t0+4*hi-(q0+qrel))-bref;
;   float l_reg=0.f;f32x16 o[4];o[0]=f32x16{};o[1]=f32x16{};o[2]=f32x16{};o[3]=f32x16{};const f32x16 negm=f32x16{};
;     ...
;   bool resc=false;
;     ...
;   f32x16 pA0,pA1,pB0,pB1;
;   int sl_prev=0,sl_cur=0,sl_next=SLOTB;
;     ...
;   DMA_K(2,2*SLOTB);
;   WAIT_BAR(4);
;   qkt(pA0,pA1,Kbase,qr,negm,r32,hi);asm volatile("s_nop 15\n\ts_nop 7":"+v"(pA0),"+v"(pA1));CMASK(pA0,pA1,0);
;   START(pA0,pA1);
;   _Pragma("unroll") for(int r=0;r<16;++r)pA1[r]=__builtin_amdgcn_exp2f(pA1[r]);
;   WAIT_BAR(0);
;   DMA_K(3,0);DMA_V(1,SLOTB);
;   ROT();
;   kload8(kf,kp0+sl_cur);
;   WAIT_BAR(3);
;     ...
;   int t=1;
;     ...
;   for(;t+5<NT;t+=2){
.LBB0_334:
	v_lshlrev_b32_e32 v34, 1, v32
	v_and_b32_e32 v254, 32, v34
	v_lshrrev_b32_e32 v34, 2, v32
	v_and_or_b32 v34, v34, 3, v250
	v_lshlrev_b32_e32 v231, 6, v34
	v_lshl_or_b32 v34, s66, 6, v250
	v_add_u32_e32 v230, s4, v253
	v_sub_u32_e32 v34, v34, v230
	v_cvt_f32_i32_e32 v34, v34
	s_waitcnt vmcnt(0) lgkmcnt(0)
	s_barrier
	s_cmp_lg_u32 0, -1
	v_add_u32_e32 v35, 0, v254
	v_fma_f32 v251, v245, v34, -s5
	v_add_f32_e32 v0, v251, v0
	v_add_f32_e32 v1, v251, v1
	v_fmac_f32_e32 v0, 0, v245
	v_add_f32_e32 v1, v245, v1
	s_mov_b64 s[4:5], 0x60000
	v_exp_f32_e32 v96, v0
	v_exp_f32_e32 v97, v1
	v_lshl_add_u64 v[0:1], v[232:233], 0, s[4:5]
	s_mov_b32 s4, m0
	s_mov_b32 m0, s79
	s_nop 0
	global_load_lds_dwordx4 v[0:1], off
	s_mov_b32 m0, s4
	s_mov_b64 s[4:5], 0x20000
	v_lshl_add_u64 v[0:1], v[234:235], 0, s[4:5]
	s_cselect_b32 s4, 0, 0
	s_add_i32 s4, s4, s16
	s_add_i32 s5, s4, 0xa000
	s_mov_b32 s16, m0
	s_mov_b32 m0, s5
	s_nop 0
	global_load_lds_dwordx4 v[0:1], off
	s_mov_b32 m0, s16
	s_mov_b64 s[16:17], 0x20080
	v_lshl_add_u64 v[0:1], v[234:235], 0, s[16:17]
	s_add_i32 s4, s4, 0xc000
	s_mov_b32 s5, m0
	s_mov_b32 m0, s4
	s_nop 0
	global_load_lds_dwordx4 v[0:1], off
	s_mov_b32 m0, s5
	ds_read_b128 v[204:207], v236 offset:8192
	ds_read_b128 v[196:199], v236 offset:8704
	ds_read_b128 v[200:203], v236 offset:10240
	ds_read_b128 v[188:191], v236 offset:10752
	ds_read_b128 v[192:195], v236 offset:12288
	ds_read_b128 v[180:183], v236 offset:12800
	ds_read_b128 v[184:187], v236 offset:14336
	ds_read_b128 v[176:179], v236 offset:14848
	v_add_f32_e32 v16, v251, v16
	v_add_f32_e32 v17, v251, v17
	v_add_f32_e32 v2, v251, v2
	v_add_f32_e32 v18, v251, v18
	v_add_f32_e32 v3, v251, v3
	v_add_f32_e32 v19, v251, v19
	v_add_f32_e32 v4, v251, v4
	v_add_f32_e32 v20, v251, v20
	v_add_f32_e32 v5, v251, v5
	v_add_f32_e32 v21, v251, v21
	v_add_f32_e32 v6, v251, v6
	v_add_f32_e32 v22, v251, v22
	v_add_f32_e32 v7, v251, v7
	v_add_f32_e32 v23, v251, v23
	v_add_f32_e32 v8, v251, v8
	v_add_f32_e32 v24, v251, v24
	v_add_f32_e32 v9, v251, v9
	v_add_f32_e32 v25, v251, v25
	v_add_f32_e32 v10, v251, v10
	v_add_f32_e32 v26, v251, v26
	v_add_f32_e32 v11, v251, v11
	v_add_f32_e32 v27, v251, v27
	v_add_f32_e32 v12, v251, v12
	v_add_f32_e32 v28, v251, v28
	v_add_f32_e32 v13, v251, v13
	v_add_f32_e32 v29, v251, v29
	v_add_f32_e32 v14, v251, v14
	v_add_f32_e32 v30, v251, v30
	v_add_f32_e32 v15, v251, v15
	v_add_f32_e32 v31, v251, v31
	v_fmac_f32_e32 v16, 0x42000000, v245
	v_fmac_f32_e32 v17, 0x42040000, v245
	v_fmac_f32_e32 v2, 2.0, v245
	v_fmac_f32_e32 v18, 0x42080000, v245
	v_fmac_f32_e32 v3, 0x40400000, v245
	v_fmac_f32_e32 v19, 0x420c0000, v245
	v_fmac_f32_e32 v4, 0x41000000, v245
	v_fmac_f32_e32 v20, 0x42200000, v245
	v_fmac_f32_e32 v5, 0x41100000, v245
	v_fmac_f32_e32 v21, 0x42240000, v245
	v_fmac_f32_e32 v6, 0x41200000, v245
	v_fmac_f32_e32 v22, 0x42280000, v245
	v_fmac_f32_e32 v7, 0x41300000, v245
	v_fmac_f32_e32 v23, 0x422c0000, v245
	v_fmac_f32_e32 v8, 0x41800000, v245
	v_fmac_f32_e32 v24, 0x42400000, v245
	v_fmac_f32_e32 v9, 0x41880000, v245
	v_fmac_f32_e32 v25, 0x42440000, v245
	v_fmac_f32_e32 v10, 0x41900000, v245
	v_fmac_f32_e32 v26, 0x42480000, v245
	v_fmac_f32_e32 v11, 0x41980000, v245
	v_fmac_f32_e32 v27, 0x424c0000, v245
	v_fmac_f32_e32 v12, 0x41c00000, v245
	v_fmac_f32_e32 v28, 0x42600000, v245
	v_fmac_f32_e32 v13, 0x41c80000, v245
	v_fmac_f32_e32 v29, 0x42640000, v245
	v_fmac_f32_e32 v14, 0x41d00000, v245
	v_fmac_f32_e32 v30, 0x42680000, v245
	v_fmac_f32_e32 v15, 0x41d80000, v245
	v_fmac_f32_e32 v31, 0x426c0000, v245
	v_exp_f32_e32 v98, v2
	v_exp_f32_e32 v99, v3
	v_exp_f32_e32 v100, v4
	v_exp_f32_e32 v101, v5
	v_exp_f32_e32 v102, v6
	v_exp_f32_e32 v103, v7
	v_exp_f32_e32 v104, v8
	v_exp_f32_e32 v105, v9
	v_exp_f32_e32 v106, v10
	v_exp_f32_e32 v107, v11
	v_exp_f32_e32 v108, v12
	v_exp_f32_e32 v109, v13
	v_exp_f32_e32 v110, v14
	v_exp_f32_e32 v111, v15
	v_exp_f32_e32 v80, v16
	v_exp_f32_e32 v81, v17
	v_exp_f32_e32 v82, v18
	v_exp_f32_e32 v83, v19
	v_exp_f32_e32 v84, v20
	v_exp_f32_e32 v85, v21
	v_exp_f32_e32 v86, v22
	v_exp_f32_e32 v87, v23
	v_exp_f32_e32 v88, v24
	v_exp_f32_e32 v89, v25
	v_exp_f32_e32 v90, v26
	v_exp_f32_e32 v91, v27
	v_exp_f32_e32 v92, v28
	v_exp_f32_e32 v93, v29
	v_exp_f32_e32 v94, v30
	v_exp_f32_e32 v95, v31
	s_waitcnt vmcnt(3) lgkmcnt(0)
	s_barrier
	v_mov_b32_e32 v241, 0x260
	s_mov_b32 s38, 1
	v_add3_u32 v240, v35, v252, v231
	v_mul_f32_e32 v229, 0x42800000, v245
	s_mov_b32 s10, 0
	s_cmp_lt_i32 s89, 7
	s_cbranch_scc1 .LBB0_505
	s_lshl_b64 s[4:5], s[64:65], 8
	s_lshl_b64 s[16:17], s[74:75], 1
	v_and_b32_e32 v0, 3, v32
	s_add_u32 s4, s16, s4
	v_lshlrev_b32_e32 v0, 4, v0
	v_mov_b32_e32 v1, v221
	s_addc_u32 s5, s17, s5
	v_lshl_add_u64 v[0:1], s[4:5], 0, v[0:1]
	s_lshl_b32 s4, s78, 9
	s_and_b32 s4, s4, 0x18000
	v_lshl_or_b32 v2, v33, 11, s4
	s_lshl_b64 s[4:5], s[72:73], 1
	s_add_u32 s10, s12, s70
	s_addc_u32 s16, s13, s71
	v_mov_b32_e32 v3, v221
	s_add_u32 s4, s10, s4
	v_lshl_add_u64 v[0:1], v[0:1], 0, v[2:3]
	s_addc_u32 s5, s16, s5
	v_mov_b32_e32 v64, 0
	v_lshl_add_u64 v[208:209], s[12:13], 0, v[0:1]
	v_lshl_add_u64 v[210:211], s[4:5], 0, v[220:221]
	s_movk_i32 s5, 0x4000
	s_movk_i32 s4, 0x2000
	s_mov_b32 s17, 0
	v_mov_b32_e32 v32, 0
	v_mov_b32_e32 v33, v64
	v_mov_b32_e32 v34, v64
	v_mov_b32_e32 v35, v64
	v_mov_b32_e32 v36, v64
	v_mov_b32_e32 v37, v64
	v_mov_b32_e32 v38, v64
	v_mov_b32_e32 v39, v64
	v_mov_b32_e32 v40, v64
	v_mov_b32_e32 v41, v64
	v_mov_b32_e32 v42, v64
	v_mov_b32_e32 v43, v64
	v_mov_b32_e32 v44, v64
	v_mov_b32_e32 v45, v64
	v_mov_b32_e32 v46, v64
	v_mov_b32_e32 v47, v64
	v_mov_b32_e32 v48, 0
	v_mov_b32_e32 v49, v64
	v_mov_b32_e32 v50, v64
	v_mov_b32_e32 v51, v64
	v_mov_b32_e32 v52, v64
	v_mov_b32_e32 v53, v64
	v_mov_b32_e32 v54, v64
	v_mov_b32_e32 v55, v64
	v_mov_b32_e32 v56, v64
	v_mov_b32_e32 v57, v64
	v_mov_b32_e32 v58, v64
	v_mov_b32_e32 v59, v64
	v_mov_b32_e32 v60, v64
	v_mov_b32_e32 v61, v64
	v_mov_b32_e32 v62, v64
	v_mov_b32_e32 v63, v64
	v_mov_b32_e32 v0, 0
	v_mov_b32_e32 v1, v64
	v_mov_b32_e32 v2, v64
	v_mov_b32_e32 v3, v64
	v_mov_b32_e32 v4, v64
	v_mov_b32_e32 v5, v64
	v_mov_b32_e32 v6, v64
	v_mov_b32_e32 v7, v64
	v_mov_b32_e32 v8, v64
	v_mov_b32_e32 v9, v64
	v_mov_b32_e32 v10, v64
	v_mov_b32_e32 v11, v64
	v_mov_b32_e32 v12, v64
	v_mov_b32_e32 v13, v64
	v_mov_b32_e32 v14, v64
	v_mov_b32_e32 v15, v64
	v_mov_b32_e32 v16, 0
	v_mov_b32_e32 v17, v64
	v_mov_b32_e32 v18, v64
	v_mov_b32_e32 v19, v64
	v_mov_b32_e32 v20, v64
	v_mov_b32_e32 v21, v64
	v_mov_b32_e32 v22, v64
	v_mov_b32_e32 v23, v64
	v_mov_b32_e32 v24, v64
	v_mov_b32_e32 v25, v64
	v_mov_b32_e32 v26, v64
	v_mov_b32_e32 v27, v64
	v_mov_b32_e32 v28, v64
	v_mov_b32_e32 v29, v64
	v_mov_b32_e32 v30, v64
	v_mov_b32_e32 v31, v64
	v_readfirstlane_b32 s32, v227
	s_nop 3
	s_cmpk_ge_u32 s32, 0x100
	s_cbranch_scc1 .Lattn_t336

.Lattn_t336:
	s_mov_b32 s10, s5
	s_mov_b32 s5, s4
	s_mov_b32 s16, s38
	v_lshl_add_u32 v212, s17, 1, v240
	ds_read_b64_tr_b16 v[214:215], v212 offset:24576
	ds_read_b64_tr_b16 v[216:217], v212 offset:25088
	v_add_f32_e32 v65, v96, v97
	v_add_f32_e32 v65, v98, v65
	v_add_f32_e32 v65, v99, v65
	v_add_f32_e32 v65, v100, v65
	v_add_f32_e32 v65, v101, v65
	v_cvt_pk_bf16_f32 v156, v96, v97
	v_cvt_pk_bf16_f32 v157, v98, v99
	s_waitcnt lgkmcnt(9)
	v_mfma_f32_32x32x16_bf16 v[128:143], v[204:207], v[172:175], 0
	ds_read_b64_tr_b16 v[204:205], v212 offset:28672
	ds_read_b64_tr_b16 v[206:207], v212 offset:29184
	v_add_f32_e32 v65, v102, v65
	v_add_f32_e32 v65, v103, v65
	v_add_f32_e32 v65, v104, v65
	v_add_f32_e32 v65, v105, v65
	v_cvt_pk_bf16_f32 v158, v100, v101
	v_cvt_pk_bf16_f32 v159, v102, v103
	s_waitcnt lgkmcnt(10)
	v_mfma_f32_32x32x16_bf16 v[112:127], v[196:199], v[172:175], 0
	ds_read_b64_tr_b16 v[196:197], v212 offset:25600
	ds_read_b64_tr_b16 v[198:199], v212 offset:26112
	v_add_f32_e32 v65, v106, v65
	v_add_f32_e32 v65, v107, v65
	v_add_f32_e32 v65, v108, v65
	v_add_f32_e32 v65, v109, v65
	v_cvt_pk_bf16_f32 v152, v104, v105
	v_cvt_pk_bf16_f32 v153, v106, v107
	s_waitcnt lgkmcnt(11)
	v_mfma_f32_32x32x16_bf16 v[128:143], v[200:203], v[168:171], v[128:143]
	ds_read_b64_tr_b16 v[74:75], v212 offset:29696
	ds_read_b64_tr_b16 v[76:77], v212 offset:30208
	v_add_f32_e32 v65, v110, v65
	v_add_f32_e32 v65, v111, v65
	v_add_f32_e32 v65, v80, v65
	v_add_f32_e32 v65, v81, v65
	v_cvt_pk_bf16_f32 v154, v108, v109
	v_cvt_pk_bf16_f32 v155, v110, v111
	s_waitcnt lgkmcnt(12)
	v_mfma_f32_32x32x16_bf16 v[112:127], v[188:191], v[168:171], v[112:127]
	ds_read_b64_tr_b16 v[66:67], v212 offset:26624
	ds_read_b64_tr_b16 v[68:69], v212 offset:27136
	v_add_f32_e32 v65, v82, v65
	v_add_f32_e32 v65, v83, v65
	v_add_f32_e32 v65, v84, v65
	v_add_f32_e32 v65, v85, v65
	v_cvt_pk_bf16_f32 v148, v80, v81
	v_cvt_pk_bf16_f32 v149, v82, v83
	s_waitcnt lgkmcnt(13)
	v_mfma_f32_32x32x16_bf16 v[128:143], v[192:195], v[164:167], v[128:143]
	ds_read_b64_tr_b16 v[96:97], v212 offset:30720
	ds_read_b64_tr_b16 v[98:99], v212 offset:31232
	v_add_f32_e32 v65, v86, v65
	v_add_f32_e32 v65, v87, v65
	v_add_f32_e32 v65, v88, v65
	v_add_f32_e32 v65, v89, v65
	v_cvt_pk_bf16_f32 v150, v84, v85
	v_cvt_pk_bf16_f32 v151, v86, v87
	s_waitcnt lgkmcnt(14)
	v_mfma_f32_32x32x16_bf16 v[112:127], v[180:183], v[164:167], v[112:127]
	ds_read_b64_tr_b16 v[82:83], v212 offset:27648
	ds_read_b64_tr_b16 v[84:85], v212 offset:28160
	v_add_f32_e32 v65, v90, v65
	v_add_f32_e32 v65, v91, v65
	v_add_f32_e32 v65, v92, v65
	v_add_f32_e32 v65, v93, v65
	v_cvt_pk_bf16_f32 v144, v88, v89
	v_cvt_pk_bf16_f32 v145, v90, v91
	s_waitcnt lgkmcnt(14)
	v_mfma_f32_32x32x16_bf16 v[128:143], v[184:187], v[160:163], v[128:143]
	ds_read_b64_tr_b16 v[70:71], v212 offset:31744
	ds_read_b64_tr_b16 v[72:73], v212 offset:32256
	v_add_f32_e32 v65, v94, v65
	v_add_f32_e32 v65, v95, v65
	v_add_f32_e32 v65, 0, v65
	v_cvt_pk_bf16_f32 v146, v92, v93
	v_cvt_pk_bf16_f32 v147, v94, v95
	v_mfma_f32_32x32x16_bf16 v[112:127], v[176:179], v[160:163], v[112:127]
	v_lshl_add_u64 v[202:203], v[210:211], 0, s[68:69]
	v_lshl_add_u64 v[78:79], v[202:203], 0, s[48:49]
	s_add_i32 s4, s4, s79
	v_lshl_add_u64 v[200:201], v[208:209], 0, s[68:69]
	s_mov_b32 s17, m0
	s_mov_b32 m0, s4
	s_nop 0
	global_load_lds_dwordx4 v[78:79], off
	s_mov_b32 m0, s17
	v_lshl_add_u64 v[78:79], v[200:201], 0, s[50:51]
	s_lshl_b32 s4, s10, 1
	s_add_i32 s4, s4, s87
	s_mov_b32 s17, m0
	s_mov_b32 m0, s4
	s_nop 0
	global_load_lds_dwordx4 v[78:79], off
	s_mov_b32 m0, s17
	v_lshl_add_u64 v[78:79], v[200:201], 0, s[52:53]
	s_addk_i32 s4, 0x2000
	s_mov_b32 s17, m0
	s_mov_b32 m0, s4
	s_nop 0
	global_load_lds_dwordx4 v[78:79], off
	s_mov_b32 m0, s17
	v_cvt_f32_u32_e32 v78, s16
	v_fma_f32 v213, v229, v78, v251
	s_waitcnt lgkmcnt(14)
	v_mfma_f32_32x32x16_bf16 v[32:47], v[156:159], v[214:217], v[32:47]
	ds_read_b64_tr_b16 v[90:91], v212 offset:32768
	ds_read_b64_tr_b16 v[92:93], v212 offset:33280
	s_waitcnt lgkmcnt(14)
	v_mfma_f32_32x32x16_bf16 v[48:63], v[156:159], v[204:207], v[48:63]
	ds_read_b64_tr_b16 v[100:101], v212 offset:36864
	ds_read_b64_tr_b16 v[102:103], v212 offset:37376
	v_add_u32_e32 v94, s10, v236
	ds_read_b128 v[86:89], v94
	ds_read_b128 v[78:81], v94 offset:512
	s_waitcnt lgkmcnt(14)
	v_mfma_f32_32x32x16_bf16 v[32:47], v[152:155], v[196:199], v[32:47]
	ds_read_b64_tr_b16 v[104:105], v212 offset:33792
	ds_read_b64_tr_b16 v[106:107], v212 offset:34304
	ds_read_b128 v[188:191], v94 offset:2048
	ds_read_b128 v[176:179], v94 offset:2560
	v_mfma_f32_32x32x16_bf16 v[48:63], v[152:155], v[74:77], v[48:63]
	ds_read_b64_tr_b16 v[108:109], v212 offset:37888
	ds_read_b64_tr_b16 v[110:111], v212 offset:38400
	ds_read_b128 v[184:187], v94 offset:4096
	ds_read_b128 v[74:77], v94 offset:4608
	s_waitcnt lgkmcnt(14)
	v_mfma_f32_32x32x16_bf16 v[32:47], v[148:151], v[66:69], v[32:47]
	ds_read_b64_tr_b16 v[192:193], v212 offset:34816
	ds_read_b64_tr_b16 v[194:195], v212 offset:35328
	ds_read_b128 v[180:183], v94 offset:6144
	ds_read_b128 v[66:69], v94 offset:6656
	v_mfma_f32_32x32x16_bf16 v[48:63], v[148:151], v[96:99], v[48:63]
	ds_read_b64_tr_b16 v[94:95], v212 offset:38912
	ds_read_b64_tr_b16 v[96:97], v212 offset:39424
	v_mfma_f32_32x32x16_bf16 v[32:47], v[144:147], v[82:85], v[32:47]
	ds_read_b64_tr_b16 v[82:83], v212 offset:35840
	ds_read_b64_tr_b16 v[84:85], v212 offset:36352
	v_mfma_f32_32x32x16_bf16 v[48:63], v[144:147], v[70:73], v[48:63]
	ds_read_b64_tr_b16 v[70:71], v212 offset:39936
	ds_read_b64_tr_b16 v[72:73], v212 offset:40448
	s_waitcnt lgkmcnt(14)
	v_mfma_f32_32x32x16_bf16 v[0:15], v[156:159], v[90:93], v[0:15]
	v_add_f32_e32 v212, v213, v128
	v_fmac_f32_e32 v212, 0, v245
	v_exp_f32_e32 v128, v212
	v_add_f32_e32 v212, v213, v129
	v_add_f32_e32 v212, v245, v212
	v_exp_f32_e32 v129, v212
	v_add_f32_e32 v212, v213, v130
	v_fmac_f32_e32 v212, 2.0, v245
	v_exp_f32_e32 v130, v212
	v_add_f32_e32 v212, v213, v131
	v_fmac_f32_e32 v212, 0x40400000, v245
	v_exp_f32_e32 v131, v212
	v_mfma_f32_32x32x16_bf16 v[16:31], v[156:159], v[100:103], v[16:31]
	v_add_f32_e32 v212, v213, v132
	v_fmac_f32_e32 v212, 0x41000000, v245
	v_exp_f32_e32 v132, v212
	v_add_f32_e32 v212, v213, v133
	v_fmac_f32_e32 v212, 0x41100000, v245
	v_exp_f32_e32 v133, v212
	v_add_f32_e32 v212, v213, v134
	v_fmac_f32_e32 v212, 0x41200000, v245
	v_exp_f32_e32 v134, v212
	v_add_f32_e32 v212, v213, v135
	v_fmac_f32_e32 v212, 0x41300000, v245
	v_exp_f32_e32 v135, v212
	v_mfma_f32_32x32x16_bf16 v[0:15], v[152:155], v[104:107], v[0:15]
	v_add_f32_e32 v212, v213, v136
	v_fmac_f32_e32 v212, 0x41800000, v245
	v_exp_f32_e32 v136, v212
	v_add_f32_e32 v212, v213, v137
	v_fmac_f32_e32 v212, 0x41880000, v245
	v_exp_f32_e32 v137, v212
	v_add_f32_e32 v212, v213, v138
	v_fmac_f32_e32 v212, 0x41900000, v245
	v_exp_f32_e32 v138, v212
	v_add_f32_e32 v212, v213, v139
	v_fmac_f32_e32 v212, 0x41980000, v245
	v_exp_f32_e32 v139, v212
	s_waitcnt lgkmcnt(12)
	v_mfma_f32_32x32x16_bf16 v[16:31], v[152:155], v[108:111], v[16:31]
	v_add_f32_e32 v212, v213, v140
	v_fmac_f32_e32 v212, 0x41c00000, v245
	v_exp_f32_e32 v140, v212
	v_add_f32_e32 v212, v213, v141
	v_fmac_f32_e32 v212, 0x41c80000, v245
	v_exp_f32_e32 v141, v212
	v_add_f32_e32 v212, v213, v142
	v_fmac_f32_e32 v212, 0x41d00000, v245
	v_exp_f32_e32 v142, v212
	v_add_f32_e32 v212, v213, v143
	v_fmac_f32_e32 v212, 0x41d80000, v245
	v_exp_f32_e32 v143, v212
	s_waitcnt lgkmcnt(8)
	v_mfma_f32_32x32x16_bf16 v[0:15], v[148:151], v[192:195], v[0:15]
	v_add_f32_e32 v212, v213, v112
	v_fmac_f32_e32 v212, 0x42000000, v245
	v_exp_f32_e32 v112, v212
	v_add_f32_e32 v212, v213, v113
	v_fmac_f32_e32 v212, 0x42040000, v245
	v_exp_f32_e32 v113, v212
	v_add_f32_e32 v212, v213, v114
	v_fmac_f32_e32 v212, 0x42080000, v245
	v_exp_f32_e32 v114, v212
	v_add_f32_e32 v212, v213, v115
	v_fmac_f32_e32 v212, 0x420c0000, v245
	v_exp_f32_e32 v115, v212
	s_waitcnt lgkmcnt(4)
	v_mfma_f32_32x32x16_bf16 v[16:31], v[148:151], v[94:97], v[16:31]
	v_add_f32_e32 v212, v213, v116
	v_fmac_f32_e32 v212, 0x42200000, v245
	v_exp_f32_e32 v116, v212
	v_add_f32_e32 v212, v213, v117
	v_fmac_f32_e32 v212, 0x42240000, v245
	v_exp_f32_e32 v117, v212
	v_add_f32_e32 v212, v213, v118
	v_fmac_f32_e32 v212, 0x42280000, v245
	v_exp_f32_e32 v118, v212
	v_add_f32_e32 v212, v213, v119
	v_fmac_f32_e32 v212, 0x422c0000, v245
	v_exp_f32_e32 v119, v212
	s_waitcnt lgkmcnt(2)
	v_mfma_f32_32x32x16_bf16 v[0:15], v[144:147], v[82:85], v[0:15]
	v_add_f32_e32 v212, v213, v120
	v_fmac_f32_e32 v212, 0x42400000, v245
	v_exp_f32_e32 v120, v212
	v_add_f32_e32 v212, v213, v121
	v_fmac_f32_e32 v212, 0x42440000, v245
	v_exp_f32_e32 v121, v212
	v_add_f32_e32 v212, v213, v122
	v_fmac_f32_e32 v212, 0x42480000, v245
	v_exp_f32_e32 v122, v212
	v_add_f32_e32 v212, v213, v123
	v_fmac_f32_e32 v212, 0x424c0000, v245
	v_exp_f32_e32 v123, v212
	s_waitcnt lgkmcnt(0)
	v_mfma_f32_32x32x16_bf16 v[16:31], v[144:147], v[70:73], v[16:31]
	v_add_f32_e32 v212, v213, v124
	v_fmac_f32_e32 v212, 0x42600000, v245
	v_exp_f32_e32 v124, v212
	v_add_f32_e32 v212, v213, v125
	v_fmac_f32_e32 v212, 0x42640000, v245
	v_exp_f32_e32 v125, v212
	v_add_f32_e32 v212, v213, v126
	v_fmac_f32_e32 v212, 0x42680000, v245
	v_exp_f32_e32 v126, v212
	v_add_f32_e32 v212, v213, v127
	v_fmac_f32_e32 v212, 0x426c0000, v245
	v_exp_f32_e32 v127, v212
	s_waitcnt vmcnt(3) lgkmcnt(0)
	s_barrier
	s_add_i32 s4, s10, 0x2000
	s_cmpk_lg_i32 s10, 0x4000
	s_cselect_b32 s4, s4, 0
	v_lshl_add_u32 v212, s5, 1, v240
	ds_read_b64_tr_b16 v[196:197], v212 offset:24576
	ds_read_b64_tr_b16 v[198:199], v212 offset:25088
	v_mfma_f32_32x32x16_bf16 v[96:111], v[86:89], v[172:175], 0
	v_add_f32_e32 v70, v128, v129
	v_add_f32_e32 v70, v130, v70
	v_add_f32_e32 v70, v131, v70
	v_add_f32_e32 v70, v132, v70
	v_add_f32_e32 v70, v133, v70
	v_cvt_pk_bf16_f32 v156, v128, v129
	v_cvt_pk_bf16_f32 v157, v130, v131
	ds_read_b64_tr_b16 v[204:205], v212 offset:28672
	ds_read_b64_tr_b16 v[206:207], v212 offset:29184
	v_mfma_f32_32x32x16_bf16 v[80:95], v[78:81], v[172:175], 0
	v_add_f32_e32 v70, v134, v70
	v_add_f32_e32 v70, v135, v70
	v_add_f32_e32 v70, v136, v70
	v_add_f32_e32 v70, v137, v70
	v_cvt_pk_bf16_f32 v158, v132, v133
	v_cvt_pk_bf16_f32 v159, v134, v135
	ds_read_b64_tr_b16 v[192:193], v212 offset:25600
	ds_read_b64_tr_b16 v[194:195], v212 offset:26112
	v_mfma_f32_32x32x16_bf16 v[96:111], v[188:191], v[168:171], v[96:111]
	v_add_f32_e32 v70, v138, v70
	v_add_f32_e32 v70, v139, v70
	v_add_f32_e32 v70, v140, v70
	v_add_f32_e32 v70, v141, v70
	v_cvt_pk_bf16_f32 v152, v136, v137
	v_cvt_pk_bf16_f32 v153, v138, v139
	ds_read_b64_tr_b16 v[132:133], v212 offset:29696
	ds_read_b64_tr_b16 v[134:135], v212 offset:30208
	v_mfma_f32_32x32x16_bf16 v[80:95], v[176:179], v[168:171], v[80:95]
	v_add_f32_e32 v70, v142, v70
	v_add_f32_e32 v70, v143, v70
	v_add_f32_e32 v70, v112, v70
	v_add_f32_e32 v70, v113, v70
	v_cvt_pk_bf16_f32 v154, v140, v141
	v_cvt_pk_bf16_f32 v155, v142, v143
	ds_read_b64_tr_b16 v[128:129], v212 offset:26624
	ds_read_b64_tr_b16 v[130:131], v212 offset:27136
	v_mfma_f32_32x32x16_bf16 v[96:111], v[184:187], v[164:167], v[96:111]
	v_add_f32_e32 v70, v114, v70
	v_add_f32_e32 v70, v115, v70
	v_add_f32_e32 v70, v116, v70
	v_add_f32_e32 v70, v117, v70
	v_cvt_pk_bf16_f32 v148, v112, v113
	v_cvt_pk_bf16_f32 v149, v114, v115
	ds_read_b64_tr_b16 v[112:113], v212 offset:30720
	ds_read_b64_tr_b16 v[114:115], v212 offset:31232
	v_mfma_f32_32x32x16_bf16 v[80:95], v[74:77], v[164:167], v[80:95]
	v_add_f32_e32 v70, v118, v70
	v_add_f32_e32 v70, v119, v70
	v_add_f32_e32 v70, v120, v70
	v_add_f32_e32 v70, v121, v70
	v_cvt_pk_bf16_f32 v150, v116, v117
	v_cvt_pk_bf16_f32 v151, v118, v119
	ds_read_b64_tr_b16 v[74:75], v212 offset:27648
	ds_read_b64_tr_b16 v[76:77], v212 offset:28160
	v_mfma_f32_32x32x16_bf16 v[96:111], v[180:183], v[160:163], v[96:111]
	v_add_f32_e32 v70, v122, v70
	v_add_f32_e32 v70, v123, v70
	v_add_f32_e32 v70, v124, v70
	v_add_f32_e32 v78, v125, v70
	v_cvt_pk_bf16_f32 v144, v120, v121
	v_cvt_pk_bf16_f32 v145, v122, v123
	ds_read_b64_tr_b16 v[70:71], v212 offset:31744
	ds_read_b64_tr_b16 v[72:73], v212 offset:32256
	v_mfma_f32_32x32x16_bf16 v[80:95], v[66:69], v[160:163], v[80:95]
	v_add_f32_e32 v66, v126, v78
	v_add_f32_e32 v66, v127, v66
	v_add_f32_e32 v78, 0, v66
	v_cvt_pk_bf16_f32 v146, v124, v125
	v_cvt_pk_bf16_f32 v147, v126, v127
	s_add_i32 s5, s10, s79
	v_lshl_add_u64 v[66:67], v[202:203], 0, s[54:55]
	s_mov_b32 s17, m0
	s_mov_b32 m0, s5
	s_nop 0
	global_load_lds_dwordx4 v[66:67], off
	s_mov_b32 m0, s17
	s_lshl_b32 s5, s4, 1
	v_lshl_add_u64 v[66:67], v[200:201], 0, s[58:59]
	s_add_i32 s5, s5, s87
	s_mov_b32 s17, m0
	s_mov_b32 m0, s5
	s_nop 0
	global_load_lds_dwordx4 v[66:67], off
	s_mov_b32 m0, s17
	s_add_i32 s17, s16, 1
	v_cvt_f32_u32_e32 v68, s17
	v_lshl_add_u64 v[66:67], v[200:201], 0, s[60:61]
	s_addk_i32 s5, 0x2000
	s_mov_b32 s17, m0
	s_mov_b32 m0, s5
	s_nop 0
	global_load_lds_dwordx4 v[66:67], off
	s_mov_b32 m0, s17
	s_add_i32 s38, s38, 2
	v_fma_f32 v79, v229, v68, v251
	s_waitcnt lgkmcnt(14)
	v_mfma_f32_32x32x16_bf16 v[32:47], v[156:159], v[196:199], v[32:47]
	ds_read_b64_tr_b16 v[66:67], v212 offset:32768
	ds_read_b64_tr_b16 v[68:69], v212 offset:33280
	s_waitcnt lgkmcnt(14)
	v_mfma_f32_32x32x16_bf16 v[48:63], v[156:159], v[204:207], v[48:63]
	ds_read_b64_tr_b16 v[116:117], v212 offset:36864
	ds_read_b64_tr_b16 v[118:119], v212 offset:37376
	v_add_u32_e32 v136, s4, v236
	ds_read_b128 v[204:207], v136
	ds_read_b128 v[196:199], v136 offset:512
	s_waitcnt lgkmcnt(14)
	v_mfma_f32_32x32x16_bf16 v[32:47], v[152:155], v[192:195], v[32:47]
	ds_read_b64_tr_b16 v[120:121], v212 offset:33792
	ds_read_b64_tr_b16 v[122:123], v212 offset:34304
	ds_read_b128 v[200:203], v136 offset:2048
	ds_read_b128 v[188:191], v136 offset:2560
	v_mfma_f32_32x32x16_bf16 v[48:63], v[152:155], v[132:135], v[48:63]
	ds_read_b64_tr_b16 v[124:125], v212 offset:37888
	ds_read_b64_tr_b16 v[126:127], v212 offset:38400
	ds_read_b128 v[192:195], v136 offset:4096
	ds_read_b128 v[180:183], v136 offset:4608
	s_waitcnt lgkmcnt(14)
	v_mfma_f32_32x32x16_bf16 v[32:47], v[148:151], v[128:131], v[32:47]
	ds_read_b64_tr_b16 v[128:129], v212 offset:34816
	ds_read_b64_tr_b16 v[130:131], v212 offset:35328
	ds_read_b128 v[184:187], v136 offset:6144
	ds_read_b128 v[176:179], v136 offset:6656
	v_mfma_f32_32x32x16_bf16 v[48:63], v[148:151], v[112:115], v[48:63]
	ds_read_b64_tr_b16 v[112:113], v212 offset:38912
	ds_read_b64_tr_b16 v[114:115], v212 offset:39424
	v_mfma_f32_32x32x16_bf16 v[32:47], v[144:147], v[74:77], v[32:47]
	ds_read_b64_tr_b16 v[74:75], v212 offset:35840
	ds_read_b64_tr_b16 v[76:77], v212 offset:36352
	v_mfma_f32_32x32x16_bf16 v[48:63], v[144:147], v[70:73], v[48:63]
	ds_read_b64_tr_b16 v[70:71], v212 offset:39936
	ds_read_b64_tr_b16 v[72:73], v212 offset:40448
	s_waitcnt lgkmcnt(14)
; #define WAIT_BAR(N) asm volatile("s_waitcnt vmcnt(" #N ") lgkmcnt(0)\n\ts_barrier":::"memory")
;   #define RESC() do{ if(resc){ asm volatile("s_waitcnt lgkmcnt(0)":::"memory"); \
;       _Pragma("unroll") for(int d_=0;d_<2;++d_) _Pragma("unroll") for(int r=0;r<16;++r)o[d_][r]*=wsf[crow(r,hi)]; } }while(0)
;   #define ROT() do{sl_prev=sl_cur;sl_cur=sl_next;sl_next=(sl_next==(NSLOT-1)*SLOTB)?0:sl_next+SLOTB;}while(0)
; template<int THRL> __device__ __forceinline__ void attn_unit(int hq,int hv,int qb,const bf16*Q,const bf16*__restrict__ K,const bf16*__restrict__ V,bf16*O,const float slope2,const int t0,const int ntiles,const bool band,float*Lout,const float bref,char*shm){
;     ...
;   int t=1;
;     ...
;   for(;t+5<NT;t+=2){
;     STEP(pB0,pB1,pA0,pA1,t,true,true,true);     WAIT_BAR(3); RESC(); ROT();
;     STEP(pA0,pA1,pB0,pB1,t+1,true,true,true);   WAIT_BAR(3); RESC(); ROT();
;   }
	v_mfma_f32_32x32x16_bf16 v[0:15], v[156:159], v[66:69], v[0:15]
	v_add_f32_e32 v212, v79, v96
	v_fmac_f32_e32 v212, 0, v245
	v_exp_f32_e32 v96, v212
	v_add_f32_e32 v212, v79, v97
	v_add_f32_e32 v212, v245, v212
	v_exp_f32_e32 v97, v212
	v_add_f32_e32 v212, v79, v98
	v_fmac_f32_e32 v212, 2.0, v245
	v_exp_f32_e32 v98, v212
	v_add_f32_e32 v212, v79, v99
	v_fmac_f32_e32 v212, 0x40400000, v245
	v_exp_f32_e32 v99, v212
	v_mfma_f32_32x32x16_bf16 v[16:31], v[156:159], v[116:119], v[16:31]
	v_add_f32_e32 v100, v79, v100
	v_fmac_f32_e32 v100, 0x41000000, v245
	v_exp_f32_e32 v100, v100
	v_add_f32_e32 v101, v79, v101
	v_fmac_f32_e32 v101, 0x41100000, v245
	v_exp_f32_e32 v101, v101
	v_add_f32_e32 v102, v79, v102
	v_fmac_f32_e32 v102, 0x41200000, v245
	v_exp_f32_e32 v102, v102
	v_add_f32_e32 v103, v79, v103
	v_fmac_f32_e32 v103, 0x41300000, v245
	v_exp_f32_e32 v103, v103
	v_mfma_f32_32x32x16_bf16 v[0:15], v[152:155], v[120:123], v[0:15]
	v_add_f32_e32 v104, v79, v104
	v_fmac_f32_e32 v104, 0x41800000, v245
	v_exp_f32_e32 v104, v104
	v_add_f32_e32 v105, v79, v105
	v_fmac_f32_e32 v105, 0x41880000, v245
	v_exp_f32_e32 v105, v105
	v_add_f32_e32 v106, v79, v106
	v_fmac_f32_e32 v106, 0x41900000, v245
	v_exp_f32_e32 v106, v106
	v_add_f32_e32 v107, v79, v107
	v_fmac_f32_e32 v107, 0x41980000, v245
	v_exp_f32_e32 v107, v107
	s_waitcnt lgkmcnt(12)
	v_mfma_f32_32x32x16_bf16 v[16:31], v[152:155], v[124:127], v[16:31]
	v_add_f32_e32 v108, v79, v108
	v_fmac_f32_e32 v108, 0x41c00000, v245
	v_exp_f32_e32 v108, v108
	v_add_f32_e32 v109, v79, v109
	v_fmac_f32_e32 v109, 0x41c80000, v245
	v_exp_f32_e32 v109, v109
	v_add_f32_e32 v110, v79, v110
	v_fmac_f32_e32 v110, 0x41d00000, v245
	v_exp_f32_e32 v110, v110
	v_add_f32_e32 v111, v79, v111
	v_fmac_f32_e32 v111, 0x41d80000, v245
	v_exp_f32_e32 v111, v111
	s_waitcnt lgkmcnt(8)
	v_mfma_f32_32x32x16_bf16 v[0:15], v[148:151], v[128:131], v[0:15]
	v_add_f32_e32 v80, v79, v80
	v_fmac_f32_e32 v80, 0x42000000, v245
	v_exp_f32_e32 v80, v80
	v_add_f32_e32 v81, v79, v81
	v_fmac_f32_e32 v81, 0x42040000, v245
	v_exp_f32_e32 v81, v81
	v_add_f32_e32 v82, v79, v82
	v_fmac_f32_e32 v82, 0x42080000, v245
	v_exp_f32_e32 v82, v82
	v_add_f32_e32 v83, v79, v83
	v_fmac_f32_e32 v83, 0x420c0000, v245
	v_exp_f32_e32 v83, v83
	s_waitcnt lgkmcnt(4)
	v_mfma_f32_32x32x16_bf16 v[16:31], v[148:151], v[112:115], v[16:31]
	v_add_f32_e32 v84, v79, v84
	v_fmac_f32_e32 v84, 0x42200000, v245
	v_exp_f32_e32 v84, v84
	v_add_f32_e32 v85, v79, v85
	v_fmac_f32_e32 v85, 0x42240000, v245
	v_exp_f32_e32 v85, v85
	v_add_f32_e32 v86, v79, v86
	v_fmac_f32_e32 v86, 0x42280000, v245
	v_exp_f32_e32 v86, v86
	v_add_f32_e32 v87, v79, v87
	v_fmac_f32_e32 v87, 0x422c0000, v245
	v_exp_f32_e32 v87, v87
	s_waitcnt lgkmcnt(2)
	v_mfma_f32_32x32x16_bf16 v[0:15], v[144:147], v[74:77], v[0:15]
	v_add_f32_e32 v212, v79, v88
	v_fmac_f32_e32 v212, 0x42400000, v245
	v_exp_f32_e32 v88, v212
	v_add_f32_e32 v212, v79, v89
	v_fmac_f32_e32 v212, 0x42440000, v245
	v_exp_f32_e32 v89, v212
	v_add_f32_e32 v212, v79, v90
	v_fmac_f32_e32 v212, 0x42480000, v245
	v_exp_f32_e32 v90, v212
	v_add_f32_e32 v212, v79, v91
	v_fmac_f32_e32 v212, 0x424c0000, v245
	v_exp_f32_e32 v91, v212
	s_waitcnt lgkmcnt(0)
	v_mfma_f32_32x32x16_bf16 v[16:31], v[144:147], v[70:73], v[16:31]
	v_add_f32_e32 v212, v79, v92
	v_fmac_f32_e32 v212, 0x42600000, v245
	v_exp_f32_e32 v92, v212
	v_add_f32_e32 v212, v79, v93
	v_fmac_f32_e32 v212, 0x42640000, v245
	v_exp_f32_e32 v93, v212
	v_add_f32_e32 v212, v79, v94
	v_fmac_f32_e32 v212, 0x42680000, v245
	v_exp_f32_e32 v94, v212
	v_add_f32_e32 v212, v79, v95
	v_fmac_f32_e32 v212, 0x426c0000, v245
	v_exp_f32_e32 v95, v212
	s_add_i32 s5, s4, 0x2000
	s_waitcnt vmcnt(3) lgkmcnt(0)
	s_barrier
	s_cmpk_lg_i32 s4, 0x4000
	v_add_f32_e32 v64, v64, v65
	s_cselect_b32 s5, s5, 0
	s_add_i32 s16, s16, 7
	v_add_f32_e32 v64, v64, v78
	v_lshl_add_u64 v[208:209], v[208:209], 0, s[42:43]
	v_lshl_add_u64 v[210:211], v[210:211], 0, s[42:43]
	s_cmp_ge_i32 s16, s89
	s_mov_b32 s17, s10
	s_cbranch_scc0 .Lattn_t336
	s_branch .LBB0_506
